# inproj remainder gemm_tile K-loop: fragments read up front, early buffer-release barrier, LDS-DMA two steps ahead interleaved with MFMAs
# speedup vs baseline: 1.1279x; 1.0046x over previous
; DI int otid() { int t = threadIdx.x; asm volatile("" : "+v"(t)); return t; }
; #define G_WAIT() { asm volatile("s_waitcnt vmcnt(0)" ::: "memory"); __syncthreads(); }
;   const int tid_full = otid(); const int tid = tid_full & 255; lds += (tid_full >> 8) * HALF_LDS;
;   const int lane = tid & 63, w = tid >> 6, l31 = lane & 31, h = lane >> 5;
;   const int wr = w >> 1, wc = w & 1;
;   const int lrow = tid >> 3, lch = (tid & 7) ^ ((tid >> 4) & 7);
;   const bf16_t* ag = A + (size_t)lrow * lda + lch * 8;
;   const bf16_t* bg = Bt + (size_t)lrow * ldb + lch * 8;
;   const size_t a32 = (size_t)32 * lda, b32 = (size_t)32 * ldb;
;   f32x16 acc[2][2];
; #pragma unroll
;   for (int i = 0; i < 2; ++i)
; #pragma unroll
;     for (int j = 0; j < 2; ++j)
; #pragma unroll
;       for (int e = 0; e < 16; ++e) acc[i][j][e] = 0.f;
;   const int nk = K >> 6;
;   const int rsw = (l31 >> 1) & 7;
;   const int aoff = (wr * 64 + l31) * 128, boff = 16384 + (wc * 64 + l31) * 128;
;   char* ldst = lds + tid * 16;
;     ...
;   G_DMA(0, 0);
;   G_WAIT();
;   for (int kt = 0; kt < nk; kt += 2) {
;     if (kt + 1 < nk) G_DMA(1, kt + 1);
; DI void phase_inproj(KP p, int l, char* lds) {
;     ...
;   for (int sp = (nfull == 0) ? lb : lb - nfull; sp >= 0 && sp < 18; sp += nfree) {
;     {
;       const int mt = 36 * xcd + 2 * sp + hb;
;       if (l == 1 && (mt % 18) >= 16) continue;
;       const int m0 = mt * 128;
;       gemm_tile(hx + (size_t)m0 * 1024, 1024, wt + (size_t)2560 * 1024, 1024, 1024, lds, [&](int m, int n, f32x4 v) {
.LBB0_330:
	s_lshl_b32 s18, s21, 1
	s_add_i32 s18, s2, s18
	s_mul_hi_i32 s19, s18, 0x38e38e39
	s_lshr_b32 s34, s19, 31
	s_ashr_i32 s19, s19, 2
	s_add_i32 s19, s19, s34
	s_mul_i32 s19, s19, 18
	s_sub_i32 s19, s18, s19
	s_cmp_gt_i32 s19, 15
	s_cselect_b64 s[34:35], -1, 0
	s_and_b64 s[34:35], s[4:5], s[34:35]
	s_and_b64 vcc, exec, s[34:35]
	s_cbranch_vccnz .LBB0_329
	s_lshl_b32 s18, s18, 7
	s_ashr_i32 s55, s54, 31
	s_ashr_i32 s19, s18, 31
	v_mov_b32_e32 v75, v196
	s_lshl_b64 s[34:35], s[54:55], 11
	s_lshl_b64 s[18:19], s[18:19], 11
	s_mov_b32 s40, 0x11000
	v_lshrrev_b32_e32 v0, 8, v75
	v_lshrrev_b32_e32 v11, 4, v75
	v_mov_b32_e32 v8, 4
	s_add_u32 s18, s50, s18
	v_mul_i32_i24_e32 v74, 0x11000, v0
	v_mad_i32_i24 v77, v0, s40, 0
	v_xor_b32_e32 v0, v11, v75
	v_lshlrev_b32_e32 v2, 8, v75
	v_lshlrev_b32_sdwa v8, v8, v75 dst_sel:DWORD dst_unused:UNUSED_PAD src0_sel:DWORD src1_sel:BYTE_0
	s_addc_u32 s19, s51, s19
	v_and_b32_e32 v2, 0xf800, v2
	v_mov_b32_e32 v3, v1
	v_lshlrev_b32_e32 v0, 4, v0
	v_add_u32_e32 v80, v77, v8
	v_lshl_add_u64 v[6:7], s[18:19], 0, v[2:3]
	v_and_b32_e32 v0, 0x70, v0
	v_add_u32_e32 v81, 0x4000, v80
	v_readfirstlane_b32 s18, v80
	v_lshl_add_u64 v[4:5], s[46:47], 0, v[2:3]
	v_lshl_add_u64 v[6:7], v[6:7], 0, v[0:1]
	s_mov_b32 m0, s18
	v_readfirstlane_b32 s18, v81
	v_add_u32_e32 v82, 0x1000, v80
	v_lshl_add_u64 v[4:5], v[4:5], 0, v[0:1]
	global_load_lds_dwordx4 v[6:7], off
	s_mov_b32 m0, s18
	s_mov_b64 s[40:41], 0x10000
	v_readfirstlane_b32 s18, v82
	v_add_u32_e32 v83, 0x5000, v80
	global_load_lds_dwordx4 v[4:5], off
	v_lshl_add_u64 v[8:9], v[6:7], 0, s[40:41]
	s_mov_b32 m0, s18
	v_readfirstlane_b32 s18, v83
	v_add_u32_e32 v84, 0x2000, v80
	global_load_lds_dwordx4 v[8:9], off
	v_lshl_add_u64 v[8:9], v[4:5], 0, s[40:41]
	s_mov_b32 m0, s18
	s_mov_b64 s[40:41], 0x20000
	v_readfirstlane_b32 s18, v84
	v_add_u32_e32 v85, 0x6000, v80
	global_load_lds_dwordx4 v[8:9], off
	v_lshl_add_u64 v[8:9], v[6:7], 0, s[40:41]
	s_mov_b32 m0, s18
	v_readfirstlane_b32 s18, v85
	v_add_u32_e32 v86, 0x3000, v80
	global_load_lds_dwordx4 v[8:9], off
	v_lshl_add_u64 v[8:9], v[4:5], 0, s[40:41]
	s_mov_b32 m0, s18
	s_mov_b64 s[40:41], 0x30000
	v_readfirstlane_b32 s18, v86
	v_add_u32_e32 v87, 0x7000, v80
	global_load_lds_dwordx4 v[8:9], off
	v_lshl_add_u64 v[6:7], v[6:7], 0, s[40:41]
	s_mov_b32 m0, s18
	v_readfirstlane_b32 s18, v87
	global_load_lds_dwordx4 v[6:7], off
	v_lshl_add_u64 v[4:5], v[4:5], 0, s[40:41]
	s_mov_b32 m0, s18
	v_and_b32_e32 v76, 31, v75
	global_load_lds_dwordx4 v[4:5], off
	v_lshrrev_b32_e32 v0, 1, v75
	v_and_or_b32 v79, v0, 64, v76
	v_lshlrev_b32_e32 v0, 7, v75
	v_bfe_u32 v78, v75, 5, 1
	v_and_b32_e32 v0, 0x2f80, v0
	v_bfe_u32 v4, v75, 1, 3
	v_add_u32_e32 v90, v77, v0
	v_bitop3_b32 v0, v78, v4, 2 bitop3:0x36
	v_lshlrev_b32_e32 v91, 4, v0
	v_bitop3_b32 v0, v78, v4, 4 bitop3:0x36
	s_add_u32 s18, s36, s34
	v_lshrrev_b32_e32 v10, 5, v75
	v_lshlrev_b32_e32 v92, 4, v0
	v_bitop3_b32 v0, v78, v4, 6 bitop3:0x36
	s_addc_u32 s19, s37, s35
	v_bitop3_b32 v5, v10, v4, 1 bitop3:0x6c
	v_lshlrev_b32_e32 v93, 4, v0
	v_bitop3_b32 v0, v11, 7, v75 bitop3:0x48
	v_lshl_add_u64 v[66:67], s[48:49], 0, v[2:3]
	v_lshl_add_u64 v[68:69], s[18:19], 0, v[2:3]
	v_mov_b32_e32 v2, 0
	v_lshlrev_b32_e32 v88, 4, v5
	v_lshl_add_u32 v89, v79, 7, v77
	v_lshlrev_b32_e32 v0, 4, v0
	v_add_u32_e32 v250, 0x8000, v80
	v_lshl_add_u64 v[248:249], v[68:69], 0, v[0:1]
	v_readfirstlane_b32 s19, v250
	s_mov_b64 s[34:35], 0x18b5180
	v_lshl_add_u64 v[248:249], v[248:249], 0, s[34:35]
	s_mov_b32 m0, s19
	s_nop 0
	global_load_lds_dwordx4 v[248:249], off
	v_add_u32_e32 v250, 0xc000, v80
	v_lshl_add_u64 v[248:249], v[66:67], 0, v[0:1]
	v_readfirstlane_b32 s19, v250
	s_mov_b64 s[34:35], 0x569180
	v_lshl_add_u64 v[248:249], v[248:249], 0, s[34:35]
	s_mov_b32 m0, s19
	s_nop 0
	global_load_lds_dwordx4 v[248:249], off
	v_add_u32_e32 v250, 0x9000, v80
	v_lshl_add_u64 v[248:249], v[68:69], 0, v[0:1]
	v_readfirstlane_b32 s19, v250
	s_mov_b64 s[34:35], 0x18c5180
	v_lshl_add_u64 v[248:249], v[248:249], 0, s[34:35]
	s_mov_b32 m0, s19
	s_nop 0
	global_load_lds_dwordx4 v[248:249], off
	v_add_u32_e32 v250, 0xd000, v80
	v_lshl_add_u64 v[248:249], v[66:67], 0, v[0:1]
	v_readfirstlane_b32 s19, v250
	s_mov_b64 s[34:35], 0x579180
	v_lshl_add_u64 v[248:249], v[248:249], 0, s[34:35]
	s_mov_b32 m0, s19
	s_nop 0
	global_load_lds_dwordx4 v[248:249], off
	v_add_u32_e32 v250, 0xa000, v80
	v_lshl_add_u64 v[248:249], v[68:69], 0, v[0:1]
	v_readfirstlane_b32 s19, v250
	s_mov_b64 s[34:35], 0x18d5180
	v_lshl_add_u64 v[248:249], v[248:249], 0, s[34:35]
	s_mov_b32 m0, s19
	s_nop 0
	global_load_lds_dwordx4 v[248:249], off
	v_add_u32_e32 v250, 0xe000, v80
	v_lshl_add_u64 v[248:249], v[66:67], 0, v[0:1]
	v_readfirstlane_b32 s19, v250
	s_mov_b64 s[34:35], 0x589180
	v_lshl_add_u64 v[248:249], v[248:249], 0, s[34:35]
	s_mov_b32 m0, s19
	s_nop 0
	global_load_lds_dwordx4 v[248:249], off
	v_add_u32_e32 v250, 0xb000, v80
	v_lshl_add_u64 v[248:249], v[68:69], 0, v[0:1]
	v_readfirstlane_b32 s19, v250
	s_mov_b64 s[34:35], 0x18e5180
	v_lshl_add_u64 v[248:249], v[248:249], 0, s[34:35]
	s_mov_b32 m0, s19
	s_nop 0
	global_load_lds_dwordx4 v[248:249], off
	v_add_u32_e32 v250, 0xf000, v80
	v_lshl_add_u64 v[248:249], v[66:67], 0, v[0:1]
	v_readfirstlane_b32 s19, v250
	s_mov_b64 s[34:35], 0x599180
	v_lshl_add_u64 v[248:249], v[248:249], 0, s[34:35]
	s_mov_b32 m0, s19
	s_nop 0
	global_load_lds_dwordx4 v[248:249], off
	s_mov_b32 s18, 0
	v_mov_b32_e32 v3, v2
	v_mov_b32_e32 v4, v2
	v_mov_b32_e32 v5, v2
	v_mov_b32_e32 v6, v2
	v_mov_b32_e32 v7, v2
	v_mov_b32_e32 v8, v2
	v_mov_b32_e32 v9, v2
	v_mov_b32_e32 v10, v2
	v_mov_b32_e32 v11, v2
	v_mov_b32_e32 v12, v2
	v_mov_b32_e32 v13, v2
	v_mov_b32_e32 v14, v2
	v_mov_b32_e32 v15, v2
	v_mov_b32_e32 v16, v2
	v_mov_b32_e32 v17, v2
	v_mov_b32_e32 v18, v2
	v_mov_b32_e32 v19, v2
	v_mov_b32_e32 v20, v2
	v_mov_b32_e32 v21, v2
	v_mov_b32_e32 v22, v2
	v_mov_b32_e32 v23, v2
	v_mov_b32_e32 v24, v2
	v_mov_b32_e32 v25, v2
	v_mov_b32_e32 v26, v2
	v_mov_b32_e32 v27, v2
	v_mov_b32_e32 v28, v2
	v_mov_b32_e32 v29, v2
	v_mov_b32_e32 v30, v2
	v_mov_b32_e32 v31, v2
	v_mov_b32_e32 v32, v2
	v_mov_b32_e32 v33, v2
	v_mov_b32_e32 v34, v2
	v_mov_b32_e32 v35, v2
	v_mov_b32_e32 v36, v2
	v_mov_b32_e32 v37, v2
	v_mov_b32_e32 v38, v2
	v_mov_b32_e32 v39, v2
	v_mov_b32_e32 v40, v2
	v_mov_b32_e32 v41, v2
	v_mov_b32_e32 v42, v2
	v_mov_b32_e32 v43, v2
	v_mov_b32_e32 v44, v2
	v_mov_b32_e32 v45, v2
	v_mov_b32_e32 v46, v2
	v_mov_b32_e32 v47, v2
	v_mov_b32_e32 v48, v2
	v_mov_b32_e32 v49, v2
	v_mov_b32_e32 v50, v2
	v_mov_b32_e32 v51, v2
	v_mov_b32_e32 v52, v2
	v_mov_b32_e32 v53, v2
	v_mov_b32_e32 v54, v2
	v_mov_b32_e32 v55, v2
	v_mov_b32_e32 v56, v2
	v_mov_b32_e32 v57, v2
	v_mov_b32_e32 v58, v2
	v_mov_b32_e32 v59, v2
	v_mov_b32_e32 v60, v2
	v_mov_b32_e32 v61, v2
	v_mov_b32_e32 v62, v2
	v_mov_b32_e32 v63, v2
	v_mov_b32_e32 v64, v2
	v_mov_b32_e32 v65, v2
	s_waitcnt vmcnt(8) lgkmcnt(0)
	s_barrier
; #define G_WAIT() { asm volatile("s_waitcnt vmcnt(0)" ::: "memory"); __syncthreads(); }
;     ...
;   G_DMA(0, 0);
;   G_WAIT();
;   for (int kt = 0; kt < nk; kt += 2) {
;     if (kt + 1 < nk) G_DMA(1, kt + 1);
;     G_COMPUTE(0);
;     G_WAIT();
;     if (kt + 1 < nk) {
;       if (kt + 2 < nk) G_DMA(0, kt + 2);
;       G_COMPUTE(1);
;       G_WAIT();
.LBB0_333:
	v_add_u32_e32 v160, v90, v88
	v_add_u32_e32 v192, v89, v88
	v_add_u32_e32 v161, v90, v91
	v_add_u32_e32 v193, v89, v91
	v_add_u32_e32 v190, v90, v92
	v_add_u32_e32 v194, v89, v92
	v_add_u32_e32 v191, v90, v93
	v_add_u32_e32 v195, v89, v93
.Lrt_loop:
	ds_read_b128 v[128:131], v160 offset:16384
	ds_read_b128 v[132:135], v160 offset:20480
	ds_read_b128 v[136:139], v192 offset:0
	ds_read_b128 v[140:143], v192 offset:4096
	ds_read_b128 v[144:147], v161 offset:16384
	ds_read_b128 v[148:151], v161 offset:20480
	ds_read_b128 v[152:155], v193 offset:0
	ds_read_b128 v[156:159], v193 offset:4096
	ds_read_b128 v[216:219], v190 offset:16384
	ds_read_b128 v[220:223], v190 offset:20480
	ds_read_b128 v[224:227], v194 offset:0
	ds_read_b128 v[228:231], v194 offset:4096
	ds_read_b128 v[232:235], v191 offset:16384
	ds_read_b128 v[236:239], v191 offset:20480
	ds_read_b128 v[240:243], v195 offset:0
	ds_read_b128 v[244:247], v195 offset:4096
	s_waitcnt lgkmcnt(0)
	s_barrier
	s_cmp_lt_u32 s18, 14
	s_cbranch_scc0 .Lrt_a_nodma
	v_mov_b32_e32 v250, v80
	v_lshl_add_u64 v[248:249], v[68:69], 0, v[0:1]
	v_readfirstlane_b32 s19, v250
	s_mov_b64 s[34:35], 0x18b5200
	v_lshl_add_u64 v[248:249], v[248:249], 0, s[34:35]
	s_mov_b32 m0, s19
	s_nop 0
	global_load_lds_dwordx4 v[248:249], off
	v_mfma_f32_32x32x16_bf16 v[50:65], v[128:131], v[136:139], v[50:65]
	v_mfma_f32_32x32x16_bf16 v[34:49], v[132:135], v[136:139], v[34:49]
	v_add_u32_e32 v250, 0x4000, v80
	v_lshl_add_u64 v[248:249], v[66:67], 0, v[0:1]
	v_readfirstlane_b32 s19, v250
	s_mov_b64 s[34:35], 0x569200
	v_lshl_add_u64 v[248:249], v[248:249], 0, s[34:35]
	s_mov_b32 m0, s19
	s_nop 0
	global_load_lds_dwordx4 v[248:249], off
	v_mfma_f32_32x32x16_bf16 v[18:33], v[128:131], v[140:143], v[18:33]
	v_mfma_f32_32x32x16_bf16 v[2:17], v[132:135], v[140:143], v[2:17]
	v_add_u32_e32 v250, 0x1000, v80
	v_lshl_add_u64 v[248:249], v[68:69], 0, v[0:1]
	v_readfirstlane_b32 s19, v250
	s_mov_b64 s[34:35], 0x18c5200
	v_lshl_add_u64 v[248:249], v[248:249], 0, s[34:35]
	s_mov_b32 m0, s19
	s_nop 0
	global_load_lds_dwordx4 v[248:249], off
	v_mfma_f32_32x32x16_bf16 v[50:65], v[144:147], v[152:155], v[50:65]
	v_mfma_f32_32x32x16_bf16 v[34:49], v[148:151], v[152:155], v[34:49]
	v_add_u32_e32 v250, 0x5000, v80
	v_lshl_add_u64 v[248:249], v[66:67], 0, v[0:1]
	v_readfirstlane_b32 s19, v250
	s_mov_b64 s[34:35], 0x579200
	v_lshl_add_u64 v[248:249], v[248:249], 0, s[34:35]
	s_mov_b32 m0, s19
	s_nop 0
	global_load_lds_dwordx4 v[248:249], off
	v_mfma_f32_32x32x16_bf16 v[18:33], v[144:147], v[156:159], v[18:33]
	v_mfma_f32_32x32x16_bf16 v[2:17], v[148:151], v[156:159], v[2:17]
	v_add_u32_e32 v250, 0x2000, v80
	v_lshl_add_u64 v[248:249], v[68:69], 0, v[0:1]
	v_readfirstlane_b32 s19, v250
	s_mov_b64 s[34:35], 0x18d5200
	v_lshl_add_u64 v[248:249], v[248:249], 0, s[34:35]
	s_mov_b32 m0, s19
	s_nop 0
	global_load_lds_dwordx4 v[248:249], off
	v_mfma_f32_32x32x16_bf16 v[50:65], v[216:219], v[224:227], v[50:65]
	v_mfma_f32_32x32x16_bf16 v[34:49], v[220:223], v[224:227], v[34:49]
	v_add_u32_e32 v250, 0x6000, v80
	v_lshl_add_u64 v[248:249], v[66:67], 0, v[0:1]
	v_readfirstlane_b32 s19, v250
	s_mov_b64 s[34:35], 0x589200
	v_lshl_add_u64 v[248:249], v[248:249], 0, s[34:35]
	s_mov_b32 m0, s19
	s_nop 0
	global_load_lds_dwordx4 v[248:249], off
	v_mfma_f32_32x32x16_bf16 v[18:33], v[216:219], v[228:231], v[18:33]
	v_mfma_f32_32x32x16_bf16 v[2:17], v[220:223], v[228:231], v[2:17]
	v_add_u32_e32 v250, 0x3000, v80
	v_lshl_add_u64 v[248:249], v[68:69], 0, v[0:1]
	v_readfirstlane_b32 s19, v250
	s_mov_b64 s[34:35], 0x18e5200
	v_lshl_add_u64 v[248:249], v[248:249], 0, s[34:35]
	s_mov_b32 m0, s19
	s_nop 0
	global_load_lds_dwordx4 v[248:249], off
	v_mfma_f32_32x32x16_bf16 v[50:65], v[232:235], v[240:243], v[50:65]
	v_mfma_f32_32x32x16_bf16 v[34:49], v[236:239], v[240:243], v[34:49]
	v_add_u32_e32 v250, 0x7000, v80
	v_lshl_add_u64 v[248:249], v[66:67], 0, v[0:1]
	v_readfirstlane_b32 s19, v250
	s_mov_b64 s[34:35], 0x599200
	v_lshl_add_u64 v[248:249], v[248:249], 0, s[34:35]
	s_mov_b32 m0, s19
	s_nop 0
	global_load_lds_dwordx4 v[248:249], off
	v_mfma_f32_32x32x16_bf16 v[18:33], v[232:235], v[244:247], v[18:33]
	v_mfma_f32_32x32x16_bf16 v[2:17], v[236:239], v[244:247], v[2:17]
	s_waitcnt vmcnt(8)
	s_barrier
	s_branch .Lrt_b
.Lrt_a_nodma:
	v_mfma_f32_32x32x16_bf16 v[50:65], v[128:131], v[136:139], v[50:65]
	v_mfma_f32_32x32x16_bf16 v[34:49], v[132:135], v[136:139], v[34:49]
	v_mfma_f32_32x32x16_bf16 v[18:33], v[128:131], v[140:143], v[18:33]
	v_mfma_f32_32x32x16_bf16 v[2:17], v[132:135], v[140:143], v[2:17]
	v_mfma_f32_32x32x16_bf16 v[50:65], v[144:147], v[152:155], v[50:65]
	v_mfma_f32_32x32x16_bf16 v[34:49], v[148:151], v[152:155], v[34:49]
	v_mfma_f32_32x32x16_bf16 v[18:33], v[144:147], v[156:159], v[18:33]
	v_mfma_f32_32x32x16_bf16 v[2:17], v[148:151], v[156:159], v[2:17]
	v_mfma_f32_32x32x16_bf16 v[50:65], v[216:219], v[224:227], v[50:65]
	v_mfma_f32_32x32x16_bf16 v[34:49], v[220:223], v[224:227], v[34:49]
	v_mfma_f32_32x32x16_bf16 v[18:33], v[216:219], v[228:231], v[18:33]
	v_mfma_f32_32x32x16_bf16 v[2:17], v[220:223], v[228:231], v[2:17]
	v_mfma_f32_32x32x16_bf16 v[50:65], v[232:235], v[240:243], v[50:65]
	v_mfma_f32_32x32x16_bf16 v[34:49], v[236:239], v[240:243], v[34:49]
	v_mfma_f32_32x32x16_bf16 v[18:33], v[232:235], v[244:247], v[18:33]
	v_mfma_f32_32x32x16_bf16 v[2:17], v[236:239], v[244:247], v[2:17]
	s_waitcnt vmcnt(0)
	s_barrier
; #define G_WAIT() { asm volatile("s_waitcnt vmcnt(0)" ::: "memory"); __syncthreads(); }
;     ...
;   G_DMA(0, 0);
;   G_WAIT();
;   for (int kt = 0; kt < nk; kt += 2) {
;     if (kt + 1 < nk) G_DMA(1, kt + 1);
;     G_COMPUTE(0);
;     G_WAIT();
;     if (kt + 1 < nk) {
;       if (kt + 2 < nk) G_DMA(0, kt + 2);
;       G_COMPUTE(1);
;       G_WAIT();
;     }
;   }
.Lrt_b:
	ds_read_b128 v[128:131], v160 offset:49152
	ds_read_b128 v[132:135], v160 offset:53248
	ds_read_b128 v[136:139], v192 offset:32768
	ds_read_b128 v[140:143], v192 offset:36864
	ds_read_b128 v[144:147], v161 offset:49152
	ds_read_b128 v[148:151], v161 offset:53248
	ds_read_b128 v[152:155], v193 offset:32768
	ds_read_b128 v[156:159], v193 offset:36864
	ds_read_b128 v[216:219], v190 offset:49152
	ds_read_b128 v[220:223], v190 offset:53248
	ds_read_b128 v[224:227], v194 offset:32768
	ds_read_b128 v[228:231], v194 offset:36864
	ds_read_b128 v[232:235], v191 offset:49152
	ds_read_b128 v[236:239], v191 offset:53248
	ds_read_b128 v[240:243], v195 offset:32768
	ds_read_b128 v[244:247], v195 offset:36864
	s_waitcnt lgkmcnt(0)
	s_barrier
	s_cmp_lt_u32 s18, 13
	s_cbranch_scc0 .Lrt_b_nodma
	v_add_u32_e32 v250, 0x8000, v80
	v_lshl_add_u64 v[248:249], v[68:69], 0, v[0:1]
	v_readfirstlane_b32 s19, v250
	s_mov_b64 s[34:35], 0x18b5280
	v_lshl_add_u64 v[248:249], v[248:249], 0, s[34:35]
	s_mov_b32 m0, s19
	s_nop 0
	global_load_lds_dwordx4 v[248:249], off
	v_mfma_f32_32x32x16_bf16 v[50:65], v[128:131], v[136:139], v[50:65]
	v_mfma_f32_32x32x16_bf16 v[34:49], v[132:135], v[136:139], v[34:49]
	v_add_u32_e32 v250, 0xc000, v80
	v_lshl_add_u64 v[248:249], v[66:67], 0, v[0:1]
	v_readfirstlane_b32 s19, v250
	s_mov_b64 s[34:35], 0x569280
	v_lshl_add_u64 v[248:249], v[248:249], 0, s[34:35]
	s_mov_b32 m0, s19
	s_nop 0
	global_load_lds_dwordx4 v[248:249], off
	v_mfma_f32_32x32x16_bf16 v[18:33], v[128:131], v[140:143], v[18:33]
	v_mfma_f32_32x32x16_bf16 v[2:17], v[132:135], v[140:143], v[2:17]
	v_add_u32_e32 v250, 0x9000, v80
	v_lshl_add_u64 v[248:249], v[68:69], 0, v[0:1]
	v_readfirstlane_b32 s19, v250
	s_mov_b64 s[34:35], 0x18c5280
	v_lshl_add_u64 v[248:249], v[248:249], 0, s[34:35]
	s_mov_b32 m0, s19
	s_nop 0
	global_load_lds_dwordx4 v[248:249], off
	v_mfma_f32_32x32x16_bf16 v[50:65], v[144:147], v[152:155], v[50:65]
	v_mfma_f32_32x32x16_bf16 v[34:49], v[148:151], v[152:155], v[34:49]
	v_add_u32_e32 v250, 0xd000, v80
	v_lshl_add_u64 v[248:249], v[66:67], 0, v[0:1]
	v_readfirstlane_b32 s19, v250
	s_mov_b64 s[34:35], 0x579280
	v_lshl_add_u64 v[248:249], v[248:249], 0, s[34:35]
	s_mov_b32 m0, s19
	s_nop 0
	global_load_lds_dwordx4 v[248:249], off
	v_mfma_f32_32x32x16_bf16 v[18:33], v[144:147], v[156:159], v[18:33]
	v_mfma_f32_32x32x16_bf16 v[2:17], v[148:151], v[156:159], v[2:17]
	v_add_u32_e32 v250, 0xa000, v80
	v_lshl_add_u64 v[248:249], v[68:69], 0, v[0:1]
	v_readfirstlane_b32 s19, v250
	s_mov_b64 s[34:35], 0x18d5280
	v_lshl_add_u64 v[248:249], v[248:249], 0, s[34:35]
	s_mov_b32 m0, s19
	s_nop 0
	global_load_lds_dwordx4 v[248:249], off
	v_mfma_f32_32x32x16_bf16 v[50:65], v[216:219], v[224:227], v[50:65]
	v_mfma_f32_32x32x16_bf16 v[34:49], v[220:223], v[224:227], v[34:49]
	v_add_u32_e32 v250, 0xe000, v80
	v_lshl_add_u64 v[248:249], v[66:67], 0, v[0:1]
	v_readfirstlane_b32 s19, v250
	s_mov_b64 s[34:35], 0x589280
	v_lshl_add_u64 v[248:249], v[248:249], 0, s[34:35]
	s_mov_b32 m0, s19
	s_nop 0
	global_load_lds_dwordx4 v[248:249], off
	v_mfma_f32_32x32x16_bf16 v[18:33], v[216:219], v[228:231], v[18:33]
	v_mfma_f32_32x32x16_bf16 v[2:17], v[220:223], v[228:231], v[2:17]
	v_add_u32_e32 v250, 0xb000, v80
	v_lshl_add_u64 v[248:249], v[68:69], 0, v[0:1]
	v_readfirstlane_b32 s19, v250
	s_mov_b64 s[34:35], 0x18e5280
	v_lshl_add_u64 v[248:249], v[248:249], 0, s[34:35]
	s_mov_b32 m0, s19
	s_nop 0
	global_load_lds_dwordx4 v[248:249], off
	v_mfma_f32_32x32x16_bf16 v[50:65], v[232:235], v[240:243], v[50:65]
	v_mfma_f32_32x32x16_bf16 v[34:49], v[236:239], v[240:243], v[34:49]
	v_add_u32_e32 v250, 0xf000, v80
	v_lshl_add_u64 v[248:249], v[66:67], 0, v[0:1]
	v_readfirstlane_b32 s19, v250
	s_mov_b64 s[34:35], 0x599280
	v_lshl_add_u64 v[248:249], v[248:249], 0, s[34:35]
	s_mov_b32 m0, s19
	s_nop 0
	global_load_lds_dwordx4 v[248:249], off
	v_mfma_f32_32x32x16_bf16 v[18:33], v[232:235], v[244:247], v[18:33]
	v_mfma_f32_32x32x16_bf16 v[2:17], v[236:239], v[244:247], v[2:17]
	s_waitcnt vmcnt(8)
	s_barrier
	v_lshl_add_u64 v[68:69], v[68:69], 0, s[22:23]
	v_lshl_add_u64 v[66:67], v[66:67], 0, s[22:23]
	s_add_i32 s18, s18, 2
	s_branch .Lrt_loop
.Lrt_b_nodma:
	v_mfma_f32_32x32x16_bf16 v[50:65], v[128:131], v[136:139], v[50:65]
	v_mfma_f32_32x32x16_bf16 v[34:49], v[132:135], v[136:139], v[34:49]
	v_mfma_f32_32x32x16_bf16 v[18:33], v[128:131], v[140:143], v[18:33]
	v_mfma_f32_32x32x16_bf16 v[2:17], v[132:135], v[140:143], v[2:17]
	v_mfma_f32_32x32x16_bf16 v[50:65], v[144:147], v[152:155], v[50:65]
	v_mfma_f32_32x32x16_bf16 v[34:49], v[148:151], v[152:155], v[34:49]
	v_mfma_f32_32x32x16_bf16 v[18:33], v[144:147], v[156:159], v[18:33]
	v_mfma_f32_32x32x16_bf16 v[2:17], v[148:151], v[156:159], v[2:17]
	v_mfma_f32_32x32x16_bf16 v[50:65], v[216:219], v[224:227], v[50:65]
	v_mfma_f32_32x32x16_bf16 v[34:49], v[220:223], v[224:227], v[34:49]
	v_mfma_f32_32x32x16_bf16 v[18:33], v[216:219], v[228:231], v[18:33]
	v_mfma_f32_32x32x16_bf16 v[2:17], v[220:223], v[228:231], v[2:17]
	v_mfma_f32_32x32x16_bf16 v[50:65], v[232:235], v[240:243], v[50:65]
	v_mfma_f32_32x32x16_bf16 v[34:49], v[236:239], v[240:243], v[34:49]
	v_mfma_f32_32x32x16_bf16 v[18:33], v[232:235], v[244:247], v[18:33]
	v_mfma_f32_32x32x16_bf16 v[2:17], v[236:239], v[244:247], v[2:17]
	s_branch .LBB0_335
